# weight conversion inside the merge phases: the 8 f32 tile loads of a transpose item issued together with counted vmcnt before the LDS writes
# baseline (speedup 1.0000x reference)
; #define LAS __attribute__((address_space(3)))
; __device__ __forceinline__ unsigned pk2(float lo, float hi) { f32x2_t v = {lo, hi}; bf16x2_t b = __builtin_convertvector(v, bf16x2_t); return __builtin_bit_cast(unsigned, b); }
; #define LDS_WAIT() asm volatile("s_waitcnt lgkmcnt(0)" ::: "memory")
; template <int MAP>
; __device__ __forceinline__ void transpose_item(const float* W, int K, int N, bf16_t* WT, int ldk, LAS float* scr, int item, int nblk, int lane) {
;     const int kb = item / nblk, nb = item % nblk, k0 = 64 * kb, n0 = 32 * nb;
;     const int cc = n0 + 4 * (lane & 7);
; #pragma unroll
;     for (int i = 0; i < 8; ++i) { const int kk = 8 * i + (lane >> 3); f32x4 v = {0.f, 0.f, 0.f, 0.f}; if (cc < N) v = *(const f32x4*)(W + (size_t)(k0 + kk) * N + cc);
;         LAS float* d = scr + kk * 33 + 4 * (lane & 7); d[0] = v.x; d[1] = v.y; d[2] = v.z; d[3] = v.w; }
;     LDS_WAIT();
;     const int c = lane & 7;
; #pragma unroll
;     for (int j = 0; j < 4; ++j) { const int n = (lane >> 3) + 8 * j; const LAS float* s = scr + (8 * c) * 33 + n;
;         u32x4 o; o.x = pk2(s[0 * 33], s[1 * 33]); o.y = pk2(s[2 * 33], s[3 * 33]); o.z = pk2(s[4 * 33], s[5 * 33]); o.w = pk2(s[6 * 33], s[7 * 33]);
;         const int dr = MAP ? swiglu_row(n0 + n) : (n0 + n);
;         *(u32x4*)(WT + (size_t)dr * ldk + k0 + 8 * c) = o; }
;     LDS_WAIT();
; }
.LBB0_93:
	s_andn2_b64 vcc, exec, s[4:5]
	v_add_u32_e32 v41, 0x420, v28
	v_add_u32_e32 v42, 0x428, v28
	v_add_u32_e32 v37, 0x840, v28
	v_add_u32_e32 v38, 0x848, v28
	v_add_u32_e32 v39, 0xc60, v28
	v_add_u32_e32 v40, 0xc68, v28
	v_add_u32_e32 v33, 0x1080, v28
	v_add_u32_e32 v34, 0x1088, v28
	v_add_u32_e32 v35, 0x14a0, v28
	v_add_u32_e32 v36, 0x14a8, v28
	v_add_u32_e32 v29, 0x18c0, v28
	v_add_u32_e32 v30, 0x18c8, v28
	v_add_u32_e32 v31, 0x1ce0, v28
	v_add_u32_e32 v32, 0x1ce8, v28
	s_cbranch_vccnz .LBB0_111
	v_readlane_b32 s0, v254, 36
	v_readlane_b32 s1, v254, 37
	s_load_dwordx2 s[0:1], s[0:1], 0x10
	s_mul_hi_i32 s4, s16, 0x2e8ba2e9
	s_movk_i32 s7, 0x5800
	s_waitcnt lgkmcnt(0)
	s_add_u32 s0, s0, s10
	s_addc_u32 s1, s1, s9
	s_lshr_b32 s5, s4, 31
	s_ashr_i32 s4, s4, 5
	s_add_i32 s5, s4, s5
	s_mul_i32 s6, s5, 0xffffea00
	s_add_i32 s6, s6, s13
	v_add_u32_e32 v2, s6, v18
	s_lshl_b32 s4, s5, 6
	v_ashrrev_i32_e32 v3, 31, v2
	v_lshl_add_u64 v[6:7], v[2:3], 2, s[0:1]
	v_add_u32_e32 v2, s4, v19
	v_mad_i64_i32 v[2:3], s[0:1], v2, s7, v[6:7]
	global_load_dwordx4 v[200:203], v[2:3], off
	v_add_u32_e32 v44, s6, v19
	s_mulk_i32 s5, 0xd400
	v_cmp_lt_i32_e32 vcc, s51, v44
	v_add_u32_e32 v43, s5, v27
	v_add_u32_e32 v2, s4, v20
	v_mad_i64_i32 v[2:3], s[0:1], v2, s7, v[6:7]
	global_load_dwordx4 v[204:207], v[2:3], off
	v_add_u32_e32 v2, s4, v21
	v_mad_i64_i32 v[2:3], s[0:1], v2, s7, v[6:7]
	global_load_dwordx4 v[208:211], v[2:3], off
	v_add_u32_e32 v2, s4, v22
	v_mad_i64_i32 v[2:3], s[0:1], v2, s7, v[6:7]
	global_load_dwordx4 v[212:215], v[2:3], off
	v_add_u32_e32 v2, s4, v23
	v_mad_i64_i32 v[2:3], s[0:1], v2, s7, v[6:7]
	global_load_dwordx4 v[216:219], v[2:3], off
	v_add_u32_e32 v2, s4, v24
	v_mad_i64_i32 v[2:3], s[0:1], v2, s7, v[6:7]
	global_load_dwordx4 v[220:223], v[2:3], off
	v_add_u32_e32 v2, s4, v25
	v_mad_i64_i32 v[2:3], s[0:1], v2, s7, v[6:7]
	global_load_dwordx4 v[224:227], v[2:3], off
	v_add_u32_e32 v2, s4, v26
	v_mad_i64_i32 v[2:3], s[0:1], v2, s7, v[6:7]
	global_load_dwordx4 v[228:231], v[2:3], off
	s_waitcnt vmcnt(7)
	ds_write2_b32 v28, v200, v201 offset1:1
	ds_write2_b32 v28, v202, v203 offset0:2 offset1:3
	s_waitcnt vmcnt(6)
	ds_write2_b32 v41, v204, v205 offset1:1
	ds_write2_b32 v42, v206, v207 offset1:1
	s_waitcnt vmcnt(5)
	ds_write2_b32 v37, v208, v209 offset1:1
	ds_write2_b32 v38, v210, v211 offset1:1
	s_waitcnt vmcnt(4)
	ds_write2_b32 v39, v212, v213 offset1:1
	ds_write2_b32 v40, v214, v215 offset1:1
	s_waitcnt vmcnt(3)
	ds_write2_b32 v33, v216, v217 offset1:1
	ds_write2_b32 v34, v218, v219 offset1:1
	s_waitcnt vmcnt(2)
	ds_write2_b32 v35, v220, v221 offset1:1
	ds_write2_b32 v36, v222, v223 offset1:1
	s_waitcnt vmcnt(1)
	ds_write2_b32 v29, v224, v225 offset1:1
	ds_write2_b32 v30, v226, v227 offset1:1
	s_waitcnt vmcnt(0)
	ds_write2_b32 v31, v228, v229 offset1:1
	ds_write2_b32 v32, v230, v231 offset1:1
	s_waitcnt lgkmcnt(0)
	ds_read2_b32 v[4:5], v0 offset1:33
	ds_read2_b32 v[6:7], v0 offset0:66 offset1:99
	ds_read2_b32 v[8:9], v0 offset0:132 offset1:165
	ds_read2_b32 v[14:15], v0 offset0:198 offset1:231
	v_and_b32_e32 v2, 0x7f, v44
	s_and_saveexec_b64 s[0:1], vcc
	s_xor_b64 s[6:7], exec, s[0:1]
	v_subrev_u32_e32 v3, 48, v43
	v_and_b32_e32 v3, 0x7fffff00, v3
	v_or3_b32 v16, v2, v3, s54
	s_andn2_saveexec_b64 s[6:7], s[6:7]
	v_add_u32_e32 v3, 0x800015d0, v43
	v_and_or_b32 v16, v3, s55, v2
	s_or_b64 exec, exec, s[6:7]
	s_ashr_i32 s5, s4, 31
	v_ashrrev_i32_e32 v17, 31, v16
	v_lshl_add_u64 v[2:3], s[4:5], 1, v[10:11]
	s_waitcnt lgkmcnt(3)
	v_cvt_pk_bf16_f32 v4, v4, v5
	s_waitcnt lgkmcnt(2)
	v_cvt_pk_bf16_f32 v5, v6, v7
	s_waitcnt lgkmcnt(1)
	v_cvt_pk_bf16_f32 v6, v8, v9
	v_lshlrev_b64 v[8:9], 11, v[16:17]
	s_waitcnt lgkmcnt(0)
	v_cvt_pk_bf16_f32 v7, v14, v15
	v_lshl_add_u64 v[8:9], v[2:3], 0, v[8:9]
	global_store_dwordx4 v[8:9], v[4:7], off
	ds_read2_b32 v[4:5], v0 offset0:8 offset1:41
	ds_read2_b32 v[6:7], v0 offset0:74 offset1:107
	ds_read2_b32 v[8:9], v0 offset0:140 offset1:173
	ds_read2_b32 v[14:15], v0 offset0:206 offset1:239
	v_add_u32_e32 v16, 8, v44
	v_cmp_lt_i32_e32 vcc, s51, v16
	v_and_b32_e32 v17, 0x7f, v16
	s_and_saveexec_b64 s[0:1], vcc
	s_xor_b64 s[4:5], exec, s[0:1]
	v_subrev_u32_e32 v16, 32, v43
	v_and_b32_e32 v16, 0x7fffff00, v16
	v_or3_b32 v16, v17, v16, s54
	s_andn2_saveexec_b64 s[4:5], s[4:5]
	v_add_u32_e32 v16, 0x800015e0, v43
	v_and_or_b32 v16, v16, s55, v17
	s_or_b64 exec, exec, s[4:5]
	v_ashrrev_i32_e32 v17, 31, v16
	s_waitcnt lgkmcnt(3)
	v_cvt_pk_bf16_f32 v4, v4, v5
	s_waitcnt lgkmcnt(2)
	v_cvt_pk_bf16_f32 v5, v6, v7
	s_waitcnt lgkmcnt(1)
	v_cvt_pk_bf16_f32 v6, v8, v9
	v_lshlrev_b64 v[8:9], 11, v[16:17]
	s_waitcnt lgkmcnt(0)
	v_cvt_pk_bf16_f32 v7, v14, v15
	v_lshl_add_u64 v[8:9], v[2:3], 0, v[8:9]
	global_store_dwordx4 v[8:9], v[4:7], off
	ds_read2_b32 v[4:5], v0 offset0:16 offset1:49
	ds_read2_b32 v[6:7], v0 offset0:82 offset1:115
	ds_read2_b32 v[8:9], v0 offset0:148 offset1:181
	ds_read2_b32 v[14:15], v0 offset0:214 offset1:247
	v_add_u32_e32 v16, 16, v44
	v_cmp_lt_i32_e32 vcc, s51, v16
	v_and_b32_e32 v17, 0x7f, v16
	s_and_saveexec_b64 s[0:1], vcc
	s_xor_b64 s[4:5], exec, s[0:1]
	v_add_u32_e32 v16, -16, v43
	v_and_b32_e32 v16, 0x7fffff00, v16
	v_or3_b32 v16, v17, v16, s54
	s_andn2_saveexec_b64 s[4:5], s[4:5]
	v_add_u32_e32 v16, 0x800015f0, v43
	v_and_or_b32 v16, v16, s55, v17
	s_or_b64 exec, exec, s[4:5]
	v_ashrrev_i32_e32 v17, 31, v16
	s_waitcnt lgkmcnt(3)
	v_cvt_pk_bf16_f32 v4, v4, v5
	s_waitcnt lgkmcnt(2)
	v_cvt_pk_bf16_f32 v5, v6, v7
	s_waitcnt lgkmcnt(1)
	v_cvt_pk_bf16_f32 v6, v8, v9
	v_lshlrev_b64 v[8:9], 11, v[16:17]
	s_waitcnt lgkmcnt(0)
	v_cvt_pk_bf16_f32 v7, v14, v15
	v_lshl_add_u64 v[8:9], v[2:3], 0, v[8:9]
	global_store_dwordx4 v[8:9], v[4:7], off
	ds_read2_b32 v[4:5], v0 offset0:24 offset1:57
	ds_read2_b32 v[6:7], v0 offset0:90 offset1:123
	ds_read2_b32 v[8:9], v0 offset0:156 offset1:189
	ds_read2_b32 v[14:15], v0 offset0:222 offset1:255
	v_add_u32_e32 v16, 24, v44
	v_cmp_lt_i32_e32 vcc, s51, v16
	v_and_b32_e32 v17, 0x7f, v16
	s_and_saveexec_b64 s[0:1], vcc
	s_xor_b64 s[4:5], exec, s[0:1]
	v_and_b32_e32 v16, 0x7fffff00, v43
	v_or3_b32 v16, v17, v16, s54
	s_andn2_saveexec_b64 s[4:5], s[4:5]
	v_add_u32_e32 v16, 0x80001600, v43
	v_and_or_b32 v16, v16, s55, v17
	s_or_b64 exec, exec, s[4:5]
	v_ashrrev_i32_e32 v17, 31, v16
	s_waitcnt lgkmcnt(3)
	v_cvt_pk_bf16_f32 v4, v4, v5
	s_waitcnt lgkmcnt(2)
	v_cvt_pk_bf16_f32 v5, v6, v7
	s_waitcnt lgkmcnt(1)
	v_cvt_pk_bf16_f32 v6, v8, v9
	v_lshlrev_b64 v[8:9], 11, v[16:17]
	s_waitcnt lgkmcnt(0)
	v_cvt_pk_bf16_f32 v7, v14, v15
	v_lshl_add_u64 v[2:3], v[2:3], 0, v[8:9]
	global_store_dwordx4 v[2:3], v[4:7], off
	s_waitcnt lgkmcnt(0)
	s_mov_b32 s17, s16

; #define LAS __attribute__((address_space(3)))
; __device__ __forceinline__ unsigned pk2(float lo, float hi) { f32x2_t v = {lo, hi}; bf16x2_t b = __builtin_convertvector(v, bf16x2_t); return __builtin_bit_cast(unsigned, b); }
; #define LDS_WAIT() asm volatile("s_waitcnt lgkmcnt(0)" ::: "memory")
; template <int MAP>
; __device__ __forceinline__ void transpose_item(const float* W, int K, int N, bf16_t* WT, int ldk, LAS float* scr, int item, int nblk, int lane) {
;     const int kb = item / nblk, nb = item % nblk, k0 = 64 * kb, n0 = 32 * nb;
;     const int cc = n0 + 4 * (lane & 7);
; #pragma unroll
;     for (int i = 0; i < 8; ++i) { const int kk = 8 * i + (lane >> 3); f32x4 v = {0.f, 0.f, 0.f, 0.f}; if (cc < N) v = *(const f32x4*)(W + (size_t)(k0 + kk) * N + cc);
;         LAS float* d = scr + kk * 33 + 4 * (lane & 7); d[0] = v.x; d[1] = v.y; d[2] = v.z; d[3] = v.w; }
;     LDS_WAIT();
;     const int c = lane & 7;
; #pragma unroll
;     for (int j = 0; j < 4; ++j) { const int n = (lane >> 3) + 8 * j; const LAS float* s = scr + (8 * c) * 33 + n;
;         u32x4 o; o.x = pk2(s[0 * 33], s[1 * 33]); o.y = pk2(s[2 * 33], s[3 * 33]); o.z = pk2(s[4 * 33], s[5 * 33]); o.w = pk2(s[6 * 33], s[7 * 33]);
;         const int dr = MAP ? swiglu_row(n0 + n) : (n0 + n);
;         *(u32x4*)(WT + (size_t)dr * ldk + k0 + 8 * c) = o; }
;     LDS_WAIT();
; }
.LBB0_128:
	s_andn2_b64 vcc, exec, s[4:5]
	v_add_u32_e32 v41, 0x420, v28
	v_add_u32_e32 v42, 0x428, v28
	v_add_u32_e32 v37, 0x840, v28
	v_add_u32_e32 v38, 0x848, v28
	v_add_u32_e32 v39, 0xc60, v28
	v_add_u32_e32 v40, 0xc68, v28
	v_add_u32_e32 v33, 0x1080, v28
	v_add_u32_e32 v34, 0x1088, v28
	v_add_u32_e32 v35, 0x14a0, v28
	v_add_u32_e32 v36, 0x14a8, v28
	v_add_u32_e32 v29, 0x18c0, v28
	v_add_u32_e32 v30, 0x18c8, v28
	v_add_u32_e32 v31, 0x1ce0, v28
	v_add_u32_e32 v32, 0x1ce8, v28
	s_cbranch_vccnz .LBB0_146
	v_readlane_b32 s0, v254, 36
	v_readlane_b32 s1, v254, 37
	s_load_dwordx2 s[0:1], s[0:1], 0xc8
	v_readlane_b32 s4, v254, 32
	s_mov_b32 s6, s4
	s_mul_i32 s4, s4, 0x1600000
	v_readlane_b32 s5, v254, 33
	s_waitcnt lgkmcnt(0)
	s_add_u32 s0, s0, s4
	s_mul_hi_i32 s4, s6, 0x1600000
	s_addc_u32 s1, s1, s4
	s_mul_hi_i32 s4, s8, 0x2e8ba2e9
	s_lshr_b32 s5, s4, 31
	s_ashr_i32 s4, s4, 5
	s_add_i32 s5, s4, s5
	s_mul_i32 s6, s5, 0xffffea00
	s_add_i32 s6, s6, s9
	v_add_u32_e32 v2, s6, v18
	s_lshl_b32 s4, s5, 6
	v_ashrrev_i32_e32 v3, 31, v2
	v_lshl_add_u64 v[6:7], v[2:3], 2, s[0:1]
	v_add_u32_e32 v2, s4, v19
	s_movk_i32 s7, 0x5800
	v_mad_i64_i32 v[2:3], s[0:1], v2, s7, v[6:7]
	global_load_dwordx4 v[200:203], v[2:3], off
	v_add_u32_e32 v44, s6, v19
	s_mulk_i32 s5, 0xd400
	v_cmp_lt_i32_e32 vcc, s51, v44
	v_add_u32_e32 v43, s5, v0
	v_add_u32_e32 v2, s4, v20
	v_mad_i64_i32 v[2:3], s[0:1], v2, s7, v[6:7]
	global_load_dwordx4 v[204:207], v[2:3], off
	v_add_u32_e32 v2, s4, v21
	v_mad_i64_i32 v[2:3], s[0:1], v2, s7, v[6:7]
	global_load_dwordx4 v[208:211], v[2:3], off
	v_add_u32_e32 v2, s4, v22
	v_mad_i64_i32 v[2:3], s[0:1], v2, s7, v[6:7]
	global_load_dwordx4 v[212:215], v[2:3], off
	v_add_u32_e32 v2, s4, v23
	v_mad_i64_i32 v[2:3], s[0:1], v2, s7, v[6:7]
	global_load_dwordx4 v[216:219], v[2:3], off
	v_add_u32_e32 v2, s4, v24
	v_mad_i64_i32 v[2:3], s[0:1], v2, s7, v[6:7]
	global_load_dwordx4 v[220:223], v[2:3], off
	v_add_u32_e32 v2, s4, v25
	v_mad_i64_i32 v[2:3], s[0:1], v2, s7, v[6:7]
	global_load_dwordx4 v[224:227], v[2:3], off
	v_add_u32_e32 v2, s4, v26
	v_mad_i64_i32 v[2:3], s[0:1], v2, s7, v[6:7]
	global_load_dwordx4 v[228:231], v[2:3], off
	s_waitcnt vmcnt(7)
	ds_write2_b32 v28, v200, v201 offset1:1
	ds_write2_b32 v28, v202, v203 offset0:2 offset1:3
	s_waitcnt vmcnt(6)
	ds_write2_b32 v41, v204, v205 offset1:1
	ds_write2_b32 v42, v206, v207 offset1:1
	s_waitcnt vmcnt(5)
	ds_write2_b32 v37, v208, v209 offset1:1
	ds_write2_b32 v38, v210, v211 offset1:1
	s_waitcnt vmcnt(4)
	ds_write2_b32 v39, v212, v213 offset1:1
	ds_write2_b32 v40, v214, v215 offset1:1
	s_waitcnt vmcnt(3)
	ds_write2_b32 v33, v216, v217 offset1:1
	ds_write2_b32 v34, v218, v219 offset1:1
	s_waitcnt vmcnt(2)
	ds_write2_b32 v35, v220, v221 offset1:1
	ds_write2_b32 v36, v222, v223 offset1:1
	s_waitcnt vmcnt(1)
	ds_write2_b32 v29, v224, v225 offset1:1
	ds_write2_b32 v30, v226, v227 offset1:1
	s_waitcnt vmcnt(0)
	ds_write2_b32 v31, v228, v229 offset1:1
	ds_write2_b32 v32, v230, v231 offset1:1
	s_waitcnt lgkmcnt(0)
	ds_read2_b32 v[4:5], v27 offset1:33
	ds_read2_b32 v[6:7], v27 offset0:66 offset1:99
	ds_read2_b32 v[8:9], v27 offset0:132 offset1:165
	ds_read2_b32 v[14:15], v27 offset0:198 offset1:231
	v_and_b32_e32 v2, 0x7f, v44
	s_and_saveexec_b64 s[0:1], vcc
	s_xor_b64 s[6:7], exec, s[0:1]
	v_subrev_u32_e32 v3, 48, v43
	v_and_b32_e32 v3, 0x7fffff00, v3
	v_or3_b32 v16, v2, v3, s54
	s_andn2_saveexec_b64 s[6:7], s[6:7]
	v_add_u32_e32 v3, 0x800015d0, v43
	v_and_or_b32 v16, v3, s55, v2
	s_or_b64 exec, exec, s[6:7]
	s_ashr_i32 s5, s4, 31
	v_ashrrev_i32_e32 v17, 31, v16
	v_lshl_add_u64 v[2:3], s[4:5], 1, v[10:11]
	s_waitcnt lgkmcnt(3)
	v_cvt_pk_bf16_f32 v4, v4, v5
	s_waitcnt lgkmcnt(2)
	v_cvt_pk_bf16_f32 v5, v6, v7
	s_waitcnt lgkmcnt(1)
	v_cvt_pk_bf16_f32 v6, v8, v9
	v_lshlrev_b64 v[8:9], 11, v[16:17]
	s_waitcnt lgkmcnt(0)
	v_cvt_pk_bf16_f32 v7, v14, v15
	v_lshl_add_u64 v[8:9], v[2:3], 0, v[8:9]
	global_store_dwordx4 v[8:9], v[4:7], off
	ds_read2_b32 v[4:5], v27 offset0:8 offset1:41
	ds_read2_b32 v[6:7], v27 offset0:74 offset1:107
	ds_read2_b32 v[8:9], v27 offset0:140 offset1:173
	ds_read2_b32 v[14:15], v27 offset0:206 offset1:239
	v_add_u32_e32 v16, 8, v44
	v_cmp_lt_i32_e32 vcc, s51, v16
	v_and_b32_e32 v17, 0x7f, v16
	s_and_saveexec_b64 s[0:1], vcc
	s_xor_b64 s[4:5], exec, s[0:1]
	v_subrev_u32_e32 v16, 32, v43
	v_and_b32_e32 v16, 0x7fffff00, v16
	v_or3_b32 v16, v17, v16, s54
	s_andn2_saveexec_b64 s[4:5], s[4:5]
	v_add_u32_e32 v16, 0x800015e0, v43
	v_and_or_b32 v16, v16, s55, v17
	s_or_b64 exec, exec, s[4:5]
	v_ashrrev_i32_e32 v17, 31, v16
	s_waitcnt lgkmcnt(3)
	v_cvt_pk_bf16_f32 v4, v4, v5
	s_waitcnt lgkmcnt(2)
	v_cvt_pk_bf16_f32 v5, v6, v7
	s_waitcnt lgkmcnt(1)
	v_cvt_pk_bf16_f32 v6, v8, v9
	v_lshlrev_b64 v[8:9], 11, v[16:17]
	s_waitcnt lgkmcnt(0)
	v_cvt_pk_bf16_f32 v7, v14, v15
	v_lshl_add_u64 v[8:9], v[2:3], 0, v[8:9]
	global_store_dwordx4 v[8:9], v[4:7], off
	ds_read2_b32 v[4:5], v27 offset0:16 offset1:49
	ds_read2_b32 v[6:7], v27 offset0:82 offset1:115
	ds_read2_b32 v[8:9], v27 offset0:148 offset1:181
	ds_read2_b32 v[14:15], v27 offset0:214 offset1:247
	v_add_u32_e32 v16, 16, v44
	v_cmp_lt_i32_e32 vcc, s51, v16
	v_and_b32_e32 v17, 0x7f, v16
	s_and_saveexec_b64 s[0:1], vcc
	s_xor_b64 s[4:5], exec, s[0:1]
	v_add_u32_e32 v16, -16, v43
	v_and_b32_e32 v16, 0x7fffff00, v16
	v_or3_b32 v16, v17, v16, s54
	s_andn2_saveexec_b64 s[4:5], s[4:5]
	v_add_u32_e32 v16, 0x800015f0, v43
	v_and_or_b32 v16, v16, s55, v17
	s_or_b64 exec, exec, s[4:5]
	v_ashrrev_i32_e32 v17, 31, v16
	s_waitcnt lgkmcnt(3)
	v_cvt_pk_bf16_f32 v4, v4, v5
	s_waitcnt lgkmcnt(2)
	v_cvt_pk_bf16_f32 v5, v6, v7
	s_waitcnt lgkmcnt(1)
	v_cvt_pk_bf16_f32 v6, v8, v9
	v_lshlrev_b64 v[8:9], 11, v[16:17]
	s_waitcnt lgkmcnt(0)
	v_cvt_pk_bf16_f32 v7, v14, v15
	v_lshl_add_u64 v[8:9], v[2:3], 0, v[8:9]
	global_store_dwordx4 v[8:9], v[4:7], off
	ds_read2_b32 v[4:5], v27 offset0:24 offset1:57
	ds_read2_b32 v[6:7], v27 offset0:90 offset1:123
	ds_read2_b32 v[8:9], v27 offset0:156 offset1:189
	ds_read2_b32 v[14:15], v27 offset0:222 offset1:255
	v_add_u32_e32 v16, 24, v44
	v_cmp_lt_i32_e32 vcc, s51, v16
	v_and_b32_e32 v17, 0x7f, v16
	s_and_saveexec_b64 s[0:1], vcc
	s_xor_b64 s[4:5], exec, s[0:1]
	v_and_b32_e32 v16, 0x7fffff00, v43
	v_or3_b32 v16, v17, v16, s54
	s_andn2_saveexec_b64 s[4:5], s[4:5]
	v_add_u32_e32 v16, 0x80001600, v43
	v_and_or_b32 v16, v16, s55, v17
	s_or_b64 exec, exec, s[4:5]
	v_ashrrev_i32_e32 v17, 31, v16
	s_waitcnt lgkmcnt(3)
	v_cvt_pk_bf16_f32 v4, v4, v5
	s_waitcnt lgkmcnt(2)
	v_cvt_pk_bf16_f32 v5, v6, v7
	s_waitcnt lgkmcnt(1)
	v_cvt_pk_bf16_f32 v6, v8, v9
	v_lshlrev_b64 v[8:9], 11, v[16:17]
	s_waitcnt lgkmcnt(0)
	v_cvt_pk_bf16_f32 v7, v14, v15
	v_lshl_add_u64 v[2:3], v[2:3], 0, v[8:9]
	global_store_dwordx4 v[2:3], v[4:7], off
	s_waitcnt lgkmcnt(0)
	s_mov_b32 s12, s8
